# SwiGLU and merge-gate epilogues regenerated with packed mul/add and interleaved pairs (no pads), delta store addresses; static prio raise in attention
# speedup vs baseline: 1.0060x; 1.0055x over previous
; __device__ __forceinline__ float sigm(float x) { return __builtin_amdgcn_rcpf(1.f + __expf(-x)); }
; __device__ __forceinline__ float gelu_tanh(float x) { return x * sigm(1.5957691216f * (x + 0.044715f * x * x * x)); }
; __device__ __forceinline__ u32x4 pack8(const float* v) { u32x4 w; w.x = cvtpk(v[0], v[1]); w.y = cvtpk(v[2], v[3]); w.z = cvtpk(v[4], v[5]); w.w = cvtpk(v[6], v[7]); return w; }
;     template <int KIND>
;     __device__ __forceinline__ void act_tile(const pg8::f32x4 (&acc)[2][2][4][2], const float (&rs)[2][4], unsigned char* w_, int row0, int colt, int statslot, int fq_) const {
;         bf16* base = (bf16*)(w_ + (KIND == 0 ? WS_U : (KIND == 1 ? WS_V : WS_MG)));
;         constexpr int ldc = KIND == 2 ? 4096 : 1024;
; #pragma unroll
;         for (int ai = 0; ai < 2; ++ai)
; #pragma unroll
;             for (int m = 0; m < 4; ++m) {
;                 const int row = row0 + ai * 128 + m * 16;
;                 float s1 = 0.f, s2 = 0.f;
; #pragma unroll
;                 for (int bj = 0; bj < 2; ++bj) {
;                     float v[8];
; #pragma unroll
;                     for (int n = 0; n < 2; ++n)
; #pragma unroll
;                         for (int j = 0; j < 4; ++j) {
;                             const float a = acc[ai][bj][m][n][j] * rs[ai][m];
;                             const float r = KIND == 2 ? sigm(a) : gelu_tanh(a);
;                             v[n * 4 + j] = r;
;                             if (KIND == 1) { s1 += r; s2 += r * r; }
;                         }
;                     *(u32x4*)(base + (size_t)row * ldc + colt + bj * 128) = pack8(v);
;     __device__ __forceinline__ void operator()(const pg8::f32x4 (&acc)[2][2][4][2], const pg8::Unit& u, int wr, int wc, int fr, int fq) const {
;     ...
;         } else if (pn < 34) {
;             if (pn < 14) act_tile<0>(acc, rs, w_, row0, (pn - 10) * 256 + wc * 32 + fq_ * 8, 0, fq_);
;             else if (pn < 18) act_tile<1>(acc, rs, w_, row0, (pn - 14) * 256 + wc * 32 + fq_ * 8, (pn - 14) * 4 + wc, fq_);
;             else act_tile<2>(acc, rs, w_, row0, (pn - 18) * 256 + wc * 32 + fq_ * 8, 0, fq_);
.LBB0_867:
	s_and_b64 vcc, exec, s[0:1]
	s_cbranch_vccz .LBB0_892
	s_cmp_gt_u32 s66, 13
	s_mov_b64 s[0:1], -1
	s_cbranch_scc0 .LBB0_890
	s_cmp_gt_u32 s66, 17
	s_cbranch_scc0 .LBB0_871
	s_lshl_b32 s0, s66, 8
	v_readlane_b32 s1, v255, 48
	s_add_i32 s0, s1, s0
	v_add_u32_e32 v134, s0, v130
	v_ashrrev_i32_e32 v135, 31, v134
	v_lshl_add_u64 v[134:135], v[134:135], 1, s[74:75]
	v_lshlrev_b64 v[136:137], 13, v[158:159]
	v_lshl_add_u64 v[134:135], v[134:135], 0, v[136:137]
	s_waitcnt lgkmcnt(0)
	v_mov_b32_e32 v198, 0xbfb8aa3b
	v_mov_b32_e32 v199, 0xbfb8aa3b
	s_mov_b64 s[0:1], 0x1d4b6800
	v_lshl_add_u64 v[196:197], v[134:135], 0, s[0:1]
	v_pk_mul_f32 v[126:127], v[126:127], v[164:165] op_sel_hi:[1,0]
	v_pk_mul_f32 v[128:129], v[128:129], v[164:165] op_sel_hi:[1,0]
	v_pk_mul_f32 v[126:127], v[126:127], v[198:199]
	v_pk_mul_f32 v[128:129], v[128:129], v[198:199]
	v_exp_f32_e32 v126, v126
	v_exp_f32_e32 v127, v127
	v_exp_f32_e32 v128, v128
	v_exp_f32_e32 v129, v129
	v_pk_add_f32 v[126:127], v[126:127], 1.0 op_sel_hi:[1,0]
	v_pk_add_f32 v[128:129], v[128:129], 1.0 op_sel_hi:[1,0]
	v_rcp_f32_e32 v126, v126
	v_rcp_f32_e32 v127, v127
	v_rcp_f32_e32 v128, v128
	v_rcp_f32_e32 v129, v129
	v_cvt_pk_bf16_f32 v188, v126, v127
	v_cvt_pk_bf16_f32 v189, v128, v129
	v_pk_mul_f32 v[122:123], v[122:123], v[164:165] op_sel_hi:[1,0]
	v_pk_mul_f32 v[124:125], v[124:125], v[164:165] op_sel_hi:[1,0]
	v_pk_mul_f32 v[122:123], v[122:123], v[198:199]
	v_pk_mul_f32 v[124:125], v[124:125], v[198:199]
	v_exp_f32_e32 v122, v122
	v_exp_f32_e32 v123, v123
	v_exp_f32_e32 v124, v124
	v_exp_f32_e32 v125, v125
	v_pk_add_f32 v[122:123], v[122:123], 1.0 op_sel_hi:[1,0]
	v_pk_add_f32 v[124:125], v[124:125], 1.0 op_sel_hi:[1,0]
	v_rcp_f32_e32 v122, v122
	v_rcp_f32_e32 v123, v123
	v_rcp_f32_e32 v124, v124
	v_rcp_f32_e32 v125, v125
	v_cvt_pk_bf16_f32 v190, v122, v123
	v_cvt_pk_bf16_f32 v191, v124, v125
	global_store_dwordx4 v[196:197], v[188:191], off
	v_pk_mul_f32 v[118:119], v[118:119], v[164:165] op_sel_hi:[1,0]
	v_pk_mul_f32 v[120:121], v[120:121], v[164:165] op_sel_hi:[1,0]
	v_pk_mul_f32 v[118:119], v[118:119], v[198:199]
	v_pk_mul_f32 v[120:121], v[120:121], v[198:199]
	v_exp_f32_e32 v118, v118
	v_exp_f32_e32 v119, v119
	v_exp_f32_e32 v120, v120
	v_exp_f32_e32 v121, v121
	v_pk_add_f32 v[118:119], v[118:119], 1.0 op_sel_hi:[1,0]
	v_pk_add_f32 v[120:121], v[120:121], 1.0 op_sel_hi:[1,0]
	v_rcp_f32_e32 v118, v118
	v_rcp_f32_e32 v119, v119
	v_rcp_f32_e32 v120, v120
	v_rcp_f32_e32 v121, v121
	v_cvt_pk_bf16_f32 v192, v118, v119
	v_cvt_pk_bf16_f32 v193, v120, v121
	v_pk_mul_f32 v[114:115], v[114:115], v[164:165] op_sel_hi:[1,0]
	v_pk_mul_f32 v[116:117], v[116:117], v[164:165] op_sel_hi:[1,0]
	v_pk_mul_f32 v[114:115], v[114:115], v[198:199]
	v_pk_mul_f32 v[116:117], v[116:117], v[198:199]
	v_exp_f32_e32 v114, v114
	v_exp_f32_e32 v115, v115
	v_exp_f32_e32 v116, v116
	v_exp_f32_e32 v117, v117
	v_pk_add_f32 v[114:115], v[114:115], 1.0 op_sel_hi:[1,0]
	v_pk_add_f32 v[116:117], v[116:117], 1.0 op_sel_hi:[1,0]
	v_rcp_f32_e32 v114, v114
	v_rcp_f32_e32 v115, v115
	v_rcp_f32_e32 v116, v116
	v_rcp_f32_e32 v117, v117
	v_cvt_pk_bf16_f32 v194, v114, v115
	v_cvt_pk_bf16_f32 v195, v116, v117
	global_store_dwordx4 v[196:197], v[192:195], off offset:256
	s_mov_b64 s[0:1], 0x1d4d6800
	v_lshl_add_u64 v[200:201], v[134:135], 0, s[0:1]
	v_pk_mul_f32 v[110:111], v[110:111], v[164:165] op_sel:[0,1]
	v_pk_mul_f32 v[112:113], v[112:113], v[164:165] op_sel:[0,1]
	v_pk_mul_f32 v[110:111], v[110:111], v[198:199]
	v_pk_mul_f32 v[112:113], v[112:113], v[198:199]
	v_exp_f32_e32 v110, v110
	v_exp_f32_e32 v111, v111
	v_exp_f32_e32 v112, v112
	v_exp_f32_e32 v113, v113
	v_pk_add_f32 v[110:111], v[110:111], 1.0 op_sel_hi:[1,0]
	v_pk_add_f32 v[112:113], v[112:113], 1.0 op_sel_hi:[1,0]
	v_rcp_f32_e32 v110, v110
	v_rcp_f32_e32 v111, v111
	v_rcp_f32_e32 v112, v112
	v_rcp_f32_e32 v113, v113
	v_cvt_pk_bf16_f32 v188, v110, v111
	v_cvt_pk_bf16_f32 v189, v112, v113
	v_pk_mul_f32 v[106:107], v[106:107], v[164:165] op_sel:[0,1]
	v_pk_mul_f32 v[108:109], v[108:109], v[164:165] op_sel:[0,1]
	v_pk_mul_f32 v[106:107], v[106:107], v[198:199]
	v_pk_mul_f32 v[108:109], v[108:109], v[198:199]
	v_exp_f32_e32 v106, v106
	v_exp_f32_e32 v107, v107
	v_exp_f32_e32 v108, v108
	v_exp_f32_e32 v109, v109
	v_pk_add_f32 v[106:107], v[106:107], 1.0 op_sel_hi:[1,0]
	v_pk_add_f32 v[108:109], v[108:109], 1.0 op_sel_hi:[1,0]
	v_rcp_f32_e32 v106, v106
	v_rcp_f32_e32 v107, v107
	v_rcp_f32_e32 v108, v108
	v_rcp_f32_e32 v109, v109
	v_cvt_pk_bf16_f32 v190, v106, v107
	v_cvt_pk_bf16_f32 v191, v108, v109
	global_store_dwordx4 v[200:201], v[188:191], off
	v_pk_mul_f32 v[102:103], v[102:103], v[164:165] op_sel:[0,1]
	v_pk_mul_f32 v[104:105], v[104:105], v[164:165] op_sel:[0,1]
	v_pk_mul_f32 v[102:103], v[102:103], v[198:199]
	v_pk_mul_f32 v[104:105], v[104:105], v[198:199]
	v_exp_f32_e32 v102, v102
	v_exp_f32_e32 v103, v103
	v_exp_f32_e32 v104, v104
	v_exp_f32_e32 v105, v105
	v_pk_add_f32 v[102:103], v[102:103], 1.0 op_sel_hi:[1,0]
	v_pk_add_f32 v[104:105], v[104:105], 1.0 op_sel_hi:[1,0]
	v_rcp_f32_e32 v102, v102
	v_rcp_f32_e32 v103, v103
	v_rcp_f32_e32 v104, v104
	v_rcp_f32_e32 v105, v105
	v_cvt_pk_bf16_f32 v192, v102, v103
	v_cvt_pk_bf16_f32 v193, v104, v105
	v_pk_mul_f32 v[98:99], v[98:99], v[164:165] op_sel:[0,1]
	v_pk_mul_f32 v[100:101], v[100:101], v[164:165] op_sel:[0,1]
	v_pk_mul_f32 v[98:99], v[98:99], v[198:199]
	v_pk_mul_f32 v[100:101], v[100:101], v[198:199]
	v_exp_f32_e32 v98, v98
	v_exp_f32_e32 v99, v99
	v_exp_f32_e32 v100, v100
	v_exp_f32_e32 v101, v101
	v_pk_add_f32 v[98:99], v[98:99], 1.0 op_sel_hi:[1,0]
	v_pk_add_f32 v[100:101], v[100:101], 1.0 op_sel_hi:[1,0]
; __device__ __forceinline__ float gelu_tanh(float x) { return x * sigm(1.5957691216f * (x + 0.044715f * x * x * x)); }
; __device__ __forceinline__ u32x4 pack8(const float* v) { u32x4 w; w.x = cvtpk(v[0], v[1]); w.y = cvtpk(v[2], v[3]); w.z = cvtpk(v[4], v[5]); w.w = cvtpk(v[6], v[7]); return w; }
; __device__ __forceinline__ float sigm(float x) { return __builtin_amdgcn_rcpf(1.f + __expf(-x)); }
;     template <int KIND>
;     __device__ __forceinline__ void act_tile(const pg8::f32x4 (&acc)[2][2][4][2], const float (&rs)[2][4], unsigned char* w_, int row0, int colt, int statslot, int fq_) const {
;         bf16* base = (bf16*)(w_ + (KIND == 0 ? WS_U : (KIND == 1 ? WS_V : WS_MG)));
;         constexpr int ldc = KIND == 2 ? 4096 : 1024;
; #pragma unroll
;         for (int ai = 0; ai < 2; ++ai)
; #pragma unroll
;             for (int m = 0; m < 4; ++m) {
;                 const int row = row0 + ai * 128 + m * 16;
;                 float s1 = 0.f, s2 = 0.f;
; #pragma unroll
;                 for (int bj = 0; bj < 2; ++bj) {
;                     float v[8];
; #pragma unroll
;                     for (int n = 0; n < 2; ++n)
; #pragma unroll
;                         for (int j = 0; j < 4; ++j) {
;                             const float a = acc[ai][bj][m][n][j] * rs[ai][m];
;                             const float r = KIND == 2 ? sigm(a) : gelu_tanh(a);
;                             v[n * 4 + j] = r;
;                             if (KIND == 1) { s1 += r; s2 += r * r; }
;                         }
;                     *(u32x4*)(base + (size_t)row * ldc + colt + bj * 128) = pack8(v);
	v_rcp_f32_e32 v98, v98
	v_rcp_f32_e32 v99, v99
	v_rcp_f32_e32 v100, v100
	v_rcp_f32_e32 v101, v101
	v_cvt_pk_bf16_f32 v194, v98, v99
	v_cvt_pk_bf16_f32 v195, v100, v101
	global_store_dwordx4 v[200:201], v[192:195], off offset:256
	s_mov_b64 s[0:1], 0x1d4f6800
	v_lshl_add_u64 v[196:197], v[134:135], 0, s[0:1]
	v_pk_mul_f32 v[94:95], v[94:95], v[162:163] op_sel_hi:[1,0]
	v_pk_mul_f32 v[96:97], v[96:97], v[162:163] op_sel_hi:[1,0]
	v_pk_mul_f32 v[94:95], v[94:95], v[198:199]
	v_pk_mul_f32 v[96:97], v[96:97], v[198:199]
	v_exp_f32_e32 v94, v94
	v_exp_f32_e32 v95, v95
	v_exp_f32_e32 v96, v96
	v_exp_f32_e32 v97, v97
	v_pk_add_f32 v[94:95], v[94:95], 1.0 op_sel_hi:[1,0]
	v_pk_add_f32 v[96:97], v[96:97], 1.0 op_sel_hi:[1,0]
	v_rcp_f32_e32 v94, v94
	v_rcp_f32_e32 v95, v95
	v_rcp_f32_e32 v96, v96
	v_rcp_f32_e32 v97, v97
	v_cvt_pk_bf16_f32 v188, v94, v95
	v_cvt_pk_bf16_f32 v189, v96, v97
	v_pk_mul_f32 v[90:91], v[90:91], v[162:163] op_sel_hi:[1,0]
	v_pk_mul_f32 v[92:93], v[92:93], v[162:163] op_sel_hi:[1,0]
	v_pk_mul_f32 v[90:91], v[90:91], v[198:199]
	v_pk_mul_f32 v[92:93], v[92:93], v[198:199]
	v_exp_f32_e32 v90, v90
	v_exp_f32_e32 v91, v91
	v_exp_f32_e32 v92, v92
	v_exp_f32_e32 v93, v93
	v_pk_add_f32 v[90:91], v[90:91], 1.0 op_sel_hi:[1,0]
	v_pk_add_f32 v[92:93], v[92:93], 1.0 op_sel_hi:[1,0]
	v_rcp_f32_e32 v90, v90
	v_rcp_f32_e32 v91, v91
	v_rcp_f32_e32 v92, v92
	v_rcp_f32_e32 v93, v93
	v_cvt_pk_bf16_f32 v190, v90, v91
	v_cvt_pk_bf16_f32 v191, v92, v93
	global_store_dwordx4 v[196:197], v[188:191], off
	v_pk_mul_f32 v[86:87], v[86:87], v[162:163] op_sel_hi:[1,0]
	v_pk_mul_f32 v[88:89], v[88:89], v[162:163] op_sel_hi:[1,0]
	v_pk_mul_f32 v[86:87], v[86:87], v[198:199]
	v_pk_mul_f32 v[88:89], v[88:89], v[198:199]
	v_exp_f32_e32 v86, v86
	v_exp_f32_e32 v87, v87
	v_exp_f32_e32 v88, v88
	v_exp_f32_e32 v89, v89
	v_pk_add_f32 v[86:87], v[86:87], 1.0 op_sel_hi:[1,0]
	v_pk_add_f32 v[88:89], v[88:89], 1.0 op_sel_hi:[1,0]
	v_rcp_f32_e32 v86, v86
	v_rcp_f32_e32 v87, v87
	v_rcp_f32_e32 v88, v88
	v_rcp_f32_e32 v89, v89
	v_cvt_pk_bf16_f32 v192, v86, v87
	v_cvt_pk_bf16_f32 v193, v88, v89
	v_pk_mul_f32 v[82:83], v[82:83], v[162:163] op_sel_hi:[1,0]
	v_pk_mul_f32 v[84:85], v[84:85], v[162:163] op_sel_hi:[1,0]
	v_pk_mul_f32 v[82:83], v[82:83], v[198:199]
	v_pk_mul_f32 v[84:85], v[84:85], v[198:199]
	v_exp_f32_e32 v82, v82
	v_exp_f32_e32 v83, v83
	v_exp_f32_e32 v84, v84
	v_exp_f32_e32 v85, v85
	v_pk_add_f32 v[82:83], v[82:83], 1.0 op_sel_hi:[1,0]
	v_pk_add_f32 v[84:85], v[84:85], 1.0 op_sel_hi:[1,0]
	v_rcp_f32_e32 v82, v82
	v_rcp_f32_e32 v83, v83
	v_rcp_f32_e32 v84, v84
	v_rcp_f32_e32 v85, v85
	v_cvt_pk_bf16_f32 v194, v82, v83
	v_cvt_pk_bf16_f32 v195, v84, v85
	global_store_dwordx4 v[196:197], v[192:195], off offset:256
	s_mov_b64 s[0:1], 0x1d516800
	v_lshl_add_u64 v[200:201], v[134:135], 0, s[0:1]
	v_pk_mul_f32 v[78:79], v[78:79], v[162:163] op_sel:[0,1]
	v_pk_mul_f32 v[80:81], v[80:81], v[162:163] op_sel:[0,1]
	v_pk_mul_f32 v[78:79], v[78:79], v[198:199]
	v_pk_mul_f32 v[80:81], v[80:81], v[198:199]
	v_exp_f32_e32 v78, v78
	v_exp_f32_e32 v79, v79
	v_exp_f32_e32 v80, v80
	v_exp_f32_e32 v81, v81
	v_pk_add_f32 v[78:79], v[78:79], 1.0 op_sel_hi:[1,0]
	v_pk_add_f32 v[80:81], v[80:81], 1.0 op_sel_hi:[1,0]
	v_rcp_f32_e32 v78, v78
	v_rcp_f32_e32 v79, v79
	v_rcp_f32_e32 v80, v80
	v_rcp_f32_e32 v81, v81
	v_cvt_pk_bf16_f32 v188, v78, v79
	v_cvt_pk_bf16_f32 v189, v80, v81
	v_pk_mul_f32 v[74:75], v[74:75], v[162:163] op_sel:[0,1]
	v_pk_mul_f32 v[76:77], v[76:77], v[162:163] op_sel:[0,1]
	v_pk_mul_f32 v[74:75], v[74:75], v[198:199]
	v_pk_mul_f32 v[76:77], v[76:77], v[198:199]
	v_exp_f32_e32 v74, v74
	v_exp_f32_e32 v75, v75
	v_exp_f32_e32 v76, v76
	v_exp_f32_e32 v77, v77
	v_pk_add_f32 v[74:75], v[74:75], 1.0 op_sel_hi:[1,0]
	v_pk_add_f32 v[76:77], v[76:77], 1.0 op_sel_hi:[1,0]
	v_rcp_f32_e32 v74, v74
	v_rcp_f32_e32 v75, v75
	v_rcp_f32_e32 v76, v76
	v_rcp_f32_e32 v77, v77
	v_cvt_pk_bf16_f32 v190, v74, v75
	v_cvt_pk_bf16_f32 v191, v76, v77
	global_store_dwordx4 v[200:201], v[188:191], off
	v_pk_mul_f32 v[70:71], v[70:71], v[162:163] op_sel:[0,1]
	v_pk_mul_f32 v[72:73], v[72:73], v[162:163] op_sel:[0,1]
	v_pk_mul_f32 v[70:71], v[70:71], v[198:199]
	v_pk_mul_f32 v[72:73], v[72:73], v[198:199]
	v_exp_f32_e32 v70, v70
	v_exp_f32_e32 v71, v71
	v_exp_f32_e32 v72, v72
	v_exp_f32_e32 v73, v73
	v_pk_add_f32 v[70:71], v[70:71], 1.0 op_sel_hi:[1,0]
	v_pk_add_f32 v[72:73], v[72:73], 1.0 op_sel_hi:[1,0]
	v_rcp_f32_e32 v70, v70
	v_rcp_f32_e32 v71, v71
	v_rcp_f32_e32 v72, v72
	v_rcp_f32_e32 v73, v73
	v_cvt_pk_bf16_f32 v192, v70, v71
	v_cvt_pk_bf16_f32 v193, v72, v73
	v_pk_mul_f32 v[66:67], v[66:67], v[162:163] op_sel:[0,1]
	v_pk_mul_f32 v[68:69], v[68:69], v[162:163] op_sel:[0,1]
	v_pk_mul_f32 v[66:67], v[66:67], v[198:199]
	v_pk_mul_f32 v[68:69], v[68:69], v[198:199]
	v_exp_f32_e32 v66, v66
	v_exp_f32_e32 v67, v67
	v_exp_f32_e32 v68, v68
	v_exp_f32_e32 v69, v69
	v_pk_add_f32 v[66:67], v[66:67], 1.0 op_sel_hi:[1,0]
	v_pk_add_f32 v[68:69], v[68:69], 1.0 op_sel_hi:[1,0]
	v_rcp_f32_e32 v66, v66
	v_rcp_f32_e32 v67, v67
	v_rcp_f32_e32 v68, v68
	v_rcp_f32_e32 v69, v69
	v_cvt_pk_bf16_f32 v194, v66, v67
	v_cvt_pk_bf16_f32 v195, v68, v69
	global_store_dwordx4 v[200:201], v[192:195], off offset:256
	s_mov_b64 s[0:1], 0x1d5b6800
	v_lshl_add_u64 v[196:197], v[134:135], 0, s[0:1]
	v_pk_mul_f32 v[62:63], v[62:63], v[160:161] op_sel_hi:[1,0]
	v_pk_mul_f32 v[64:65], v[64:65], v[160:161] op_sel_hi:[1,0]
	v_pk_mul_f32 v[62:63], v[62:63], v[198:199]
	v_pk_mul_f32 v[64:65], v[64:65], v[198:199]
	v_exp_f32_e32 v62, v62
	v_exp_f32_e32 v63, v63
	v_exp_f32_e32 v64, v64
	v_exp_f32_e32 v65, v65
; __device__ __forceinline__ float gelu_tanh(float x) { return x * sigm(1.5957691216f * (x + 0.044715f * x * x * x)); }
; __device__ __forceinline__ u32x4 pack8(const float* v) { u32x4 w; w.x = cvtpk(v[0], v[1]); w.y = cvtpk(v[2], v[3]); w.z = cvtpk(v[4], v[5]); w.w = cvtpk(v[6], v[7]); return w; }
; __device__ __forceinline__ float sigm(float x) { return __builtin_amdgcn_rcpf(1.f + __expf(-x)); }
;     template <int KIND>
;     __device__ __forceinline__ void act_tile(const pg8::f32x4 (&acc)[2][2][4][2], const float (&rs)[2][4], unsigned char* w_, int row0, int colt, int statslot, int fq_) const {
;         bf16* base = (bf16*)(w_ + (KIND == 0 ? WS_U : (KIND == 1 ? WS_V : WS_MG)));
;         constexpr int ldc = KIND == 2 ? 4096 : 1024;
; #pragma unroll
;         for (int ai = 0; ai < 2; ++ai)
; #pragma unroll
;             for (int m = 0; m < 4; ++m) {
;                 const int row = row0 + ai * 128 + m * 16;
;                 float s1 = 0.f, s2 = 0.f;
; #pragma unroll
;                 for (int bj = 0; bj < 2; ++bj) {
;                     float v[8];
; #pragma unroll
;                     for (int n = 0; n < 2; ++n)
; #pragma unroll
;                         for (int j = 0; j < 4; ++j) {
;                             const float a = acc[ai][bj][m][n][j] * rs[ai][m];
;                             const float r = KIND == 2 ? sigm(a) : gelu_tanh(a);
;                             v[n * 4 + j] = r;
;                             if (KIND == 1) { s1 += r; s2 += r * r; }
;                         }
;                     *(u32x4*)(base + (size_t)row * ldc + colt + bj * 128) = pack8(v);
	v_pk_add_f32 v[62:63], v[62:63], 1.0 op_sel_hi:[1,0]
	v_pk_add_f32 v[64:65], v[64:65], 1.0 op_sel_hi:[1,0]
	v_rcp_f32_e32 v62, v62
	v_rcp_f32_e32 v63, v63
	v_rcp_f32_e32 v64, v64
	v_rcp_f32_e32 v65, v65
	v_cvt_pk_bf16_f32 v188, v62, v63
	v_cvt_pk_bf16_f32 v189, v64, v65
	v_pk_mul_f32 v[58:59], v[58:59], v[160:161] op_sel_hi:[1,0]
	v_pk_mul_f32 v[60:61], v[60:61], v[160:161] op_sel_hi:[1,0]
	v_pk_mul_f32 v[58:59], v[58:59], v[198:199]
	v_pk_mul_f32 v[60:61], v[60:61], v[198:199]
	v_exp_f32_e32 v58, v58
	v_exp_f32_e32 v59, v59
	v_exp_f32_e32 v60, v60
	v_exp_f32_e32 v61, v61
	v_pk_add_f32 v[58:59], v[58:59], 1.0 op_sel_hi:[1,0]
	v_pk_add_f32 v[60:61], v[60:61], 1.0 op_sel_hi:[1,0]
	v_rcp_f32_e32 v58, v58
	v_rcp_f32_e32 v59, v59
	v_rcp_f32_e32 v60, v60
	v_rcp_f32_e32 v61, v61
	v_cvt_pk_bf16_f32 v190, v58, v59
	v_cvt_pk_bf16_f32 v191, v60, v61
	global_store_dwordx4 v[196:197], v[188:191], off
	v_pk_mul_f32 v[54:55], v[54:55], v[160:161] op_sel_hi:[1,0]
	v_pk_mul_f32 v[56:57], v[56:57], v[160:161] op_sel_hi:[1,0]
	v_pk_mul_f32 v[54:55], v[54:55], v[198:199]
	v_pk_mul_f32 v[56:57], v[56:57], v[198:199]
	v_exp_f32_e32 v54, v54
	v_exp_f32_e32 v55, v55
	v_exp_f32_e32 v56, v56
	v_exp_f32_e32 v57, v57
	v_pk_add_f32 v[54:55], v[54:55], 1.0 op_sel_hi:[1,0]
	v_pk_add_f32 v[56:57], v[56:57], 1.0 op_sel_hi:[1,0]
	v_rcp_f32_e32 v54, v54
	v_rcp_f32_e32 v55, v55
	v_rcp_f32_e32 v56, v56
	v_rcp_f32_e32 v57, v57
	v_cvt_pk_bf16_f32 v192, v54, v55
	v_cvt_pk_bf16_f32 v193, v56, v57
	v_pk_mul_f32 v[50:51], v[50:51], v[160:161] op_sel_hi:[1,0]
	v_pk_mul_f32 v[52:53], v[52:53], v[160:161] op_sel_hi:[1,0]
	v_pk_mul_f32 v[50:51], v[50:51], v[198:199]
	v_pk_mul_f32 v[52:53], v[52:53], v[198:199]
	v_exp_f32_e32 v50, v50
	v_exp_f32_e32 v51, v51
	v_exp_f32_e32 v52, v52
	v_exp_f32_e32 v53, v53
	v_pk_add_f32 v[50:51], v[50:51], 1.0 op_sel_hi:[1,0]
	v_pk_add_f32 v[52:53], v[52:53], 1.0 op_sel_hi:[1,0]
	v_rcp_f32_e32 v50, v50
	v_rcp_f32_e32 v51, v51
	v_rcp_f32_e32 v52, v52
	v_rcp_f32_e32 v53, v53
	v_cvt_pk_bf16_f32 v194, v50, v51
	v_cvt_pk_bf16_f32 v195, v52, v53
	global_store_dwordx4 v[196:197], v[192:195], off offset:256
	s_mov_b64 s[0:1], 0x1d5d6800
	v_lshl_add_u64 v[200:201], v[134:135], 0, s[0:1]
	v_pk_mul_f32 v[46:47], v[46:47], v[160:161] op_sel:[0,1]
	v_pk_mul_f32 v[48:49], v[48:49], v[160:161] op_sel:[0,1]
	v_pk_mul_f32 v[46:47], v[46:47], v[198:199]
	v_pk_mul_f32 v[48:49], v[48:49], v[198:199]
	v_exp_f32_e32 v46, v46
	v_exp_f32_e32 v47, v47
	v_exp_f32_e32 v48, v48
	v_exp_f32_e32 v49, v49
	v_pk_add_f32 v[46:47], v[46:47], 1.0 op_sel_hi:[1,0]
	v_pk_add_f32 v[48:49], v[48:49], 1.0 op_sel_hi:[1,0]
	v_rcp_f32_e32 v46, v46
	v_rcp_f32_e32 v47, v47
	v_rcp_f32_e32 v48, v48
	v_rcp_f32_e32 v49, v49
	v_cvt_pk_bf16_f32 v188, v46, v47
	v_cvt_pk_bf16_f32 v189, v48, v49
	v_pk_mul_f32 v[42:43], v[42:43], v[160:161] op_sel:[0,1]
	v_pk_mul_f32 v[44:45], v[44:45], v[160:161] op_sel:[0,1]
	v_pk_mul_f32 v[42:43], v[42:43], v[198:199]
	v_pk_mul_f32 v[44:45], v[44:45], v[198:199]
	v_exp_f32_e32 v42, v42
	v_exp_f32_e32 v43, v43
	v_exp_f32_e32 v44, v44
	v_exp_f32_e32 v45, v45
	v_pk_add_f32 v[42:43], v[42:43], 1.0 op_sel_hi:[1,0]
	v_pk_add_f32 v[44:45], v[44:45], 1.0 op_sel_hi:[1,0]
	v_rcp_f32_e32 v42, v42
	v_rcp_f32_e32 v43, v43
	v_rcp_f32_e32 v44, v44
	v_rcp_f32_e32 v45, v45
	v_cvt_pk_bf16_f32 v190, v42, v43
	v_cvt_pk_bf16_f32 v191, v44, v45
	global_store_dwordx4 v[200:201], v[188:191], off
	v_pk_mul_f32 v[38:39], v[38:39], v[160:161] op_sel:[0,1]
	v_pk_mul_f32 v[40:41], v[40:41], v[160:161] op_sel:[0,1]
	v_pk_mul_f32 v[38:39], v[38:39], v[198:199]
	v_pk_mul_f32 v[40:41], v[40:41], v[198:199]
	v_exp_f32_e32 v38, v38
	v_exp_f32_e32 v39, v39
	v_exp_f32_e32 v40, v40
	v_exp_f32_e32 v41, v41
	v_pk_add_f32 v[38:39], v[38:39], 1.0 op_sel_hi:[1,0]
	v_pk_add_f32 v[40:41], v[40:41], 1.0 op_sel_hi:[1,0]
	v_rcp_f32_e32 v38, v38
	v_rcp_f32_e32 v39, v39
	v_rcp_f32_e32 v40, v40
	v_rcp_f32_e32 v41, v41
	v_cvt_pk_bf16_f32 v192, v38, v39
	v_cvt_pk_bf16_f32 v193, v40, v41
	v_pk_mul_f32 v[34:35], v[34:35], v[160:161] op_sel:[0,1]
	v_pk_mul_f32 v[36:37], v[36:37], v[160:161] op_sel:[0,1]
	v_pk_mul_f32 v[34:35], v[34:35], v[198:199]
	v_pk_mul_f32 v[36:37], v[36:37], v[198:199]
	v_exp_f32_e32 v34, v34
	v_exp_f32_e32 v35, v35
	v_exp_f32_e32 v36, v36
	v_exp_f32_e32 v37, v37
	v_pk_add_f32 v[34:35], v[34:35], 1.0 op_sel_hi:[1,0]
	v_pk_add_f32 v[36:37], v[36:37], 1.0 op_sel_hi:[1,0]
	v_rcp_f32_e32 v34, v34
	v_rcp_f32_e32 v35, v35
	v_rcp_f32_e32 v36, v36
	v_rcp_f32_e32 v37, v37
	v_cvt_pk_bf16_f32 v194, v34, v35
	v_cvt_pk_bf16_f32 v195, v36, v37
	global_store_dwordx4 v[200:201], v[192:195], off offset:256
	s_mov_b64 s[0:1], 0x1d5f6800
	v_lshl_add_u64 v[196:197], v[134:135], 0, s[0:1]
	v_pk_mul_f32 v[30:31], v[30:31], v[132:133] op_sel_hi:[1,0]
; __device__ __forceinline__ float gelu_tanh(float x) { return x * sigm(1.5957691216f * (x + 0.044715f * x * x * x)); }
; __device__ __forceinline__ u32x4 pack8(const float* v) { u32x4 w; w.x = cvtpk(v[0], v[1]); w.y = cvtpk(v[2], v[3]); w.z = cvtpk(v[4], v[5]); w.w = cvtpk(v[6], v[7]); return w; }
; __device__ __forceinline__ float sigm(float x) { return __builtin_amdgcn_rcpf(1.f + __expf(-x)); }
;     template <int KIND>
;     __device__ __forceinline__ void act_tile(const pg8::f32x4 (&acc)[2][2][4][2], const float (&rs)[2][4], unsigned char* w_, int row0, int colt, int statslot, int fq_) const {
;         bf16* base = (bf16*)(w_ + (KIND == 0 ? WS_U : (KIND == 1 ? WS_V : WS_MG)));
;         constexpr int ldc = KIND == 2 ? 4096 : 1024;
; #pragma unroll
;         for (int ai = 0; ai < 2; ++ai)
; #pragma unroll
;             for (int m = 0; m < 4; ++m) {
;                 const int row = row0 + ai * 128 + m * 16;
;                 float s1 = 0.f, s2 = 0.f;
; #pragma unroll
;                 for (int bj = 0; bj < 2; ++bj) {
;                     float v[8];
; #pragma unroll
;                     for (int n = 0; n < 2; ++n)
; #pragma unroll
;                         for (int j = 0; j < 4; ++j) {
;                             const float a = acc[ai][bj][m][n][j] * rs[ai][m];
;                             const float r = KIND == 2 ? sigm(a) : gelu_tanh(a);
;                             v[n * 4 + j] = r;
;                             if (KIND == 1) { s1 += r; s2 += r * r; }
;                         }
;                     *(u32x4*)(base + (size_t)row * ldc + colt + bj * 128) = pack8(v);
	v_pk_mul_f32 v[32:33], v[32:33], v[132:133] op_sel_hi:[1,0]
	v_pk_mul_f32 v[30:31], v[30:31], v[198:199]
	v_pk_mul_f32 v[32:33], v[32:33], v[198:199]
	v_exp_f32_e32 v30, v30
	v_exp_f32_e32 v31, v31
	v_exp_f32_e32 v32, v32
	v_exp_f32_e32 v33, v33
	v_pk_add_f32 v[30:31], v[30:31], 1.0 op_sel_hi:[1,0]
	v_pk_add_f32 v[32:33], v[32:33], 1.0 op_sel_hi:[1,0]
	v_rcp_f32_e32 v30, v30
	v_rcp_f32_e32 v31, v31
	v_rcp_f32_e32 v32, v32
	v_rcp_f32_e32 v33, v33
	v_cvt_pk_bf16_f32 v188, v30, v31
	v_cvt_pk_bf16_f32 v189, v32, v33
	v_pk_mul_f32 v[26:27], v[26:27], v[132:133] op_sel_hi:[1,0]
	v_pk_mul_f32 v[28:29], v[28:29], v[132:133] op_sel_hi:[1,0]
	v_pk_mul_f32 v[26:27], v[26:27], v[198:199]
	v_pk_mul_f32 v[28:29], v[28:29], v[198:199]
	v_exp_f32_e32 v26, v26
	v_exp_f32_e32 v27, v27
	v_exp_f32_e32 v28, v28
	v_exp_f32_e32 v29, v29
	v_pk_add_f32 v[26:27], v[26:27], 1.0 op_sel_hi:[1,0]
	v_pk_add_f32 v[28:29], v[28:29], 1.0 op_sel_hi:[1,0]
	v_rcp_f32_e32 v26, v26
	v_rcp_f32_e32 v27, v27
	v_rcp_f32_e32 v28, v28
	v_rcp_f32_e32 v29, v29
	v_cvt_pk_bf16_f32 v190, v26, v27
	v_cvt_pk_bf16_f32 v191, v28, v29
	global_store_dwordx4 v[196:197], v[188:191], off
	v_pk_mul_f32 v[22:23], v[22:23], v[132:133] op_sel_hi:[1,0]
	v_pk_mul_f32 v[24:25], v[24:25], v[132:133] op_sel_hi:[1,0]
	v_pk_mul_f32 v[22:23], v[22:23], v[198:199]
	v_pk_mul_f32 v[24:25], v[24:25], v[198:199]
	v_exp_f32_e32 v22, v22
	v_exp_f32_e32 v23, v23
	v_exp_f32_e32 v24, v24
	v_exp_f32_e32 v25, v25
	v_pk_add_f32 v[22:23], v[22:23], 1.0 op_sel_hi:[1,0]
	v_pk_add_f32 v[24:25], v[24:25], 1.0 op_sel_hi:[1,0]
	v_rcp_f32_e32 v22, v22
	v_rcp_f32_e32 v23, v23
	v_rcp_f32_e32 v24, v24
	v_rcp_f32_e32 v25, v25
	v_cvt_pk_bf16_f32 v192, v22, v23
	v_cvt_pk_bf16_f32 v193, v24, v25
	v_pk_mul_f32 v[18:19], v[18:19], v[132:133] op_sel_hi:[1,0]
	v_pk_mul_f32 v[20:21], v[20:21], v[132:133] op_sel_hi:[1,0]
	v_pk_mul_f32 v[18:19], v[18:19], v[198:199]
	v_pk_mul_f32 v[20:21], v[20:21], v[198:199]
	v_exp_f32_e32 v18, v18
	v_exp_f32_e32 v19, v19
	v_exp_f32_e32 v20, v20
	v_exp_f32_e32 v21, v21
	v_pk_add_f32 v[18:19], v[18:19], 1.0 op_sel_hi:[1,0]
	v_pk_add_f32 v[20:21], v[20:21], 1.0 op_sel_hi:[1,0]
	v_rcp_f32_e32 v18, v18
	v_rcp_f32_e32 v19, v19
	v_rcp_f32_e32 v20, v20
	v_rcp_f32_e32 v21, v21
	v_cvt_pk_bf16_f32 v194, v18, v19
	v_cvt_pk_bf16_f32 v195, v20, v21
	global_store_dwordx4 v[196:197], v[192:195], off offset:256
	s_mov_b64 s[0:1], 0x1d616800
	v_lshl_add_u64 v[200:201], v[134:135], 0, s[0:1]
	v_pk_mul_f32 v[14:15], v[14:15], v[132:133] op_sel:[0,1]
	v_pk_mul_f32 v[16:17], v[16:17], v[132:133] op_sel:[0,1]
	v_pk_mul_f32 v[14:15], v[14:15], v[198:199]
	v_pk_mul_f32 v[16:17], v[16:17], v[198:199]
	v_exp_f32_e32 v14, v14
	v_exp_f32_e32 v15, v15
	v_exp_f32_e32 v16, v16
	v_exp_f32_e32 v17, v17
	v_pk_add_f32 v[14:15], v[14:15], 1.0 op_sel_hi:[1,0]
	v_pk_add_f32 v[16:17], v[16:17], 1.0 op_sel_hi:[1,0]
	v_rcp_f32_e32 v14, v14
	v_rcp_f32_e32 v15, v15
	v_rcp_f32_e32 v16, v16
	v_rcp_f32_e32 v17, v17
	v_cvt_pk_bf16_f32 v188, v14, v15
	v_cvt_pk_bf16_f32 v189, v16, v17
	v_pk_mul_f32 v[10:11], v[10:11], v[132:133] op_sel:[0,1]
	v_pk_mul_f32 v[12:13], v[12:13], v[132:133] op_sel:[0,1]
	v_pk_mul_f32 v[10:11], v[10:11], v[198:199]
	v_pk_mul_f32 v[12:13], v[12:13], v[198:199]
	v_exp_f32_e32 v10, v10
	v_exp_f32_e32 v11, v11
	v_exp_f32_e32 v12, v12
	v_exp_f32_e32 v13, v13
	v_pk_add_f32 v[10:11], v[10:11], 1.0 op_sel_hi:[1,0]
	v_pk_add_f32 v[12:13], v[12:13], 1.0 op_sel_hi:[1,0]
	v_rcp_f32_e32 v10, v10
	v_rcp_f32_e32 v11, v11
	v_rcp_f32_e32 v12, v12
	v_rcp_f32_e32 v13, v13
	v_cvt_pk_bf16_f32 v190, v10, v11
	v_cvt_pk_bf16_f32 v191, v12, v13
	global_store_dwordx4 v[200:201], v[188:191], off
	v_pk_mul_f32 v[6:7], v[6:7], v[132:133] op_sel:[0,1]
	v_pk_mul_f32 v[8:9], v[8:9], v[132:133] op_sel:[0,1]
	v_pk_mul_f32 v[6:7], v[6:7], v[198:199]
	v_pk_mul_f32 v[8:9], v[8:9], v[198:199]
	v_exp_f32_e32 v6, v6
	v_exp_f32_e32 v7, v7
	v_exp_f32_e32 v8, v8
	v_exp_f32_e32 v9, v9
	v_pk_add_f32 v[6:7], v[6:7], 1.0 op_sel_hi:[1,0]
	v_pk_add_f32 v[8:9], v[8:9], 1.0 op_sel_hi:[1,0]
	v_rcp_f32_e32 v6, v6
	v_rcp_f32_e32 v7, v7
	v_rcp_f32_e32 v8, v8
	v_rcp_f32_e32 v9, v9
	v_cvt_pk_bf16_f32 v192, v6, v7
	v_cvt_pk_bf16_f32 v193, v8, v9
	v_pk_mul_f32 v[2:3], v[2:3], v[132:133] op_sel:[0,1]
	v_pk_mul_f32 v[4:5], v[4:5], v[132:133] op_sel:[0,1]
	v_pk_mul_f32 v[2:3], v[2:3], v[198:199]
	v_pk_mul_f32 v[4:5], v[4:5], v[198:199]
	v_exp_f32_e32 v2, v2
	v_exp_f32_e32 v3, v3
	v_exp_f32_e32 v4, v4
	v_exp_f32_e32 v5, v5
	v_pk_add_f32 v[2:3], v[2:3], 1.0 op_sel_hi:[1,0]
	v_pk_add_f32 v[4:5], v[4:5], 1.0 op_sel_hi:[1,0]
	v_rcp_f32_e32 v2, v2
	v_rcp_f32_e32 v3, v3
	v_rcp_f32_e32 v4, v4
	v_rcp_f32_e32 v5, v5
	v_cvt_pk_bf16_f32 v194, v2, v3
	v_cvt_pk_bf16_f32 v195, v4, v5
	global_store_dwordx4 v[200:201], v[192:195], off offset:256
	s_mov_b64 s[0:1], 0

; __device__ __forceinline__ u32x4 pack8(const float* v) { u32x4 w; w.x = cvtpk(v[0], v[1]); w.y = cvtpk(v[2], v[3]); w.z = cvtpk(v[4], v[5]); w.w = cvtpk(v[6], v[7]); return w; }
; __device__ __forceinline__ float sigm(float x) { return __builtin_amdgcn_rcpf(1.f + __expf(-x)); }
; __device__ __forceinline__ float siluf_(float x) { return x * sigm(x); }
;     __device__ __forceinline__ void operator()(const pg8::f32x4 (&acc)[2][2][4][2], const pg8::Unit& u, int wr, int wc, int fr, int fq) const {
;     ...
;         bf16* O = (bf16*)(w_ + WS_HFF);
;         const int row0 = u.pm * 256 + wr * 64 + fr_, col0 = u.pn * 128 + wc * 32 + fq_ * 8;
;         EPI_RSTD(rs)
; #pragma unroll
;         for (int ai = 0; ai < 2; ++ai)
; #pragma unroll
;             for (int m = 0; m < 4; ++m) {
;                 float v[8]; const float r = rs[ai][m];
; #pragma unroll
;                 for (int n = 0; n < 2; ++n)
; #pragma unroll
;                     for (int j = 0; j < 4; ++j) v[n * 4 + j] = siluf_(acc[ai][0][m][n][j] * r) * (acc[ai][1][m][n][j] * r);
;                 *(u32x4*)(O + (size_t)(row0 + ai * 128 + m * 16) * FF + col0) = pack8(v);
;             }
.LBB0_1400:
	s_lshl_b32 s6, s65, 7
	s_or_b32 s6, s6, s34
	v_lshl_add_u32 v132, v184, 3, s6
	v_ashrrev_i32_e32 v133, 31, v132
	v_lshl_add_u64 v[132:133], v[132:133], 1, s[20:21]
	s_mov_b64 s[6:7], 0x18cb4800
	v_lshl_add_u64 v[132:133], v[132:133], 0, s[6:7]
	v_mov_b32_e32 v198, 0xbfb8aa3b
	v_mov_b32_e32 v199, 0xbfb8aa3b
	v_mad_u64_u32 v[138:139], s[6:7], v176, s84, v[132:133]
	v_mov_b32_e32 v140, v139
	v_mad_u64_u32 v[140:141], s[6:7], v177, s84, v[140:141]
	v_mov_b32_e32 v139, v140
	v_pk_mul_f32 v[126:127], v[126:127], v[174:175] op_sel:[0,1]
	v_pk_mul_f32 v[128:129], v[128:129], v[174:175] op_sel:[0,1]
	v_pk_mul_f32 v[122:123], v[122:123], v[174:175] op_sel:[0,1]
	v_pk_mul_f32 v[124:125], v[124:125], v[174:175] op_sel:[0,1]
	v_pk_mul_f32 v[134:135], v[126:127], v[198:199]
	v_pk_mul_f32 v[136:137], v[128:129], v[198:199]
	v_exp_f32_e32 v134, v134
	v_exp_f32_e32 v135, v135
	v_exp_f32_e32 v136, v136
	v_exp_f32_e32 v137, v137
	v_pk_add_f32 v[134:135], v[134:135], 1.0 op_sel_hi:[1,0]
	v_pk_add_f32 v[136:137], v[136:137], 1.0 op_sel_hi:[1,0]
	v_rcp_f32_e32 v134, v134
	v_rcp_f32_e32 v135, v135
	v_rcp_f32_e32 v136, v136
	v_rcp_f32_e32 v137, v137
	v_pk_mul_f32 v[126:127], v[126:127], v[134:135]
	v_pk_mul_f32 v[128:129], v[128:129], v[136:137]
	v_pk_mul_f32 v[122:123], v[122:123], v[126:127]
	v_pk_mul_f32 v[124:125], v[124:125], v[128:129]
	v_cvt_pk_bf16_f32 v188, v122, v123
	v_cvt_pk_bf16_f32 v189, v124, v125
	v_pk_mul_f32 v[118:119], v[118:119], v[174:175] op_sel:[0,1]
	v_pk_mul_f32 v[120:121], v[120:121], v[174:175] op_sel:[0,1]
	v_pk_mul_f32 v[114:115], v[114:115], v[174:175] op_sel:[0,1]
	v_pk_mul_f32 v[116:117], v[116:117], v[174:175] op_sel:[0,1]
	v_pk_mul_f32 v[134:135], v[118:119], v[198:199]
	v_pk_mul_f32 v[136:137], v[120:121], v[198:199]
	v_exp_f32_e32 v134, v134
	v_exp_f32_e32 v135, v135
	v_exp_f32_e32 v136, v136
	v_exp_f32_e32 v137, v137
	v_pk_add_f32 v[134:135], v[134:135], 1.0 op_sel_hi:[1,0]
	v_pk_add_f32 v[136:137], v[136:137], 1.0 op_sel_hi:[1,0]
	v_rcp_f32_e32 v134, v134
	v_rcp_f32_e32 v135, v135
	v_rcp_f32_e32 v136, v136
	v_rcp_f32_e32 v137, v137
	v_pk_mul_f32 v[118:119], v[118:119], v[134:135]
	v_pk_mul_f32 v[120:121], v[120:121], v[136:137]
	v_pk_mul_f32 v[114:115], v[114:115], v[118:119]
	v_pk_mul_f32 v[116:117], v[116:117], v[120:121]
	v_cvt_pk_bf16_f32 v190, v114, v115
	v_cvt_pk_bf16_f32 v191, v116, v117
	global_store_dwordx4 v[138:139], v[188:191], off
	s_lshl_b32 s6, s84, 4
	s_mov_b32 s7, 0
	v_lshl_add_u64 v[196:197], v[138:139], 0, s[6:7]
	v_pk_mul_f32 v[110:111], v[110:111], v[174:175] op_sel_hi:[1,0]
	v_pk_mul_f32 v[112:113], v[112:113], v[174:175] op_sel_hi:[1,0]
	v_pk_mul_f32 v[106:107], v[106:107], v[174:175] op_sel_hi:[1,0]
	v_pk_mul_f32 v[108:109], v[108:109], v[174:175] op_sel_hi:[1,0]
	v_pk_mul_f32 v[134:135], v[110:111], v[198:199]
	v_pk_mul_f32 v[136:137], v[112:113], v[198:199]
	v_exp_f32_e32 v134, v134
	v_exp_f32_e32 v135, v135
	v_exp_f32_e32 v136, v136
	v_exp_f32_e32 v137, v137
	v_pk_add_f32 v[134:135], v[134:135], 1.0 op_sel_hi:[1,0]
	v_pk_add_f32 v[136:137], v[136:137], 1.0 op_sel_hi:[1,0]
	v_rcp_f32_e32 v134, v134
	v_rcp_f32_e32 v135, v135
	v_rcp_f32_e32 v136, v136
	v_rcp_f32_e32 v137, v137
	v_pk_mul_f32 v[110:111], v[110:111], v[134:135]
	v_pk_mul_f32 v[112:113], v[112:113], v[136:137]
	v_pk_mul_f32 v[106:107], v[106:107], v[110:111]
	v_pk_mul_f32 v[108:109], v[108:109], v[112:113]
	v_cvt_pk_bf16_f32 v192, v106, v107
	v_cvt_pk_bf16_f32 v193, v108, v109
	v_pk_mul_f32 v[102:103], v[102:103], v[174:175] op_sel_hi:[1,0]
	v_pk_mul_f32 v[104:105], v[104:105], v[174:175] op_sel_hi:[1,0]
	v_pk_mul_f32 v[98:99], v[98:99], v[174:175] op_sel_hi:[1,0]
	v_pk_mul_f32 v[100:101], v[100:101], v[174:175] op_sel_hi:[1,0]
	v_pk_mul_f32 v[134:135], v[102:103], v[198:199]
	v_pk_mul_f32 v[136:137], v[104:105], v[198:199]
	v_exp_f32_e32 v134, v134
	v_exp_f32_e32 v135, v135
	v_exp_f32_e32 v136, v136
	v_exp_f32_e32 v137, v137
	v_pk_add_f32 v[134:135], v[134:135], 1.0 op_sel_hi:[1,0]
	v_pk_add_f32 v[136:137], v[136:137], 1.0 op_sel_hi:[1,0]
	v_rcp_f32_e32 v134, v134
	v_rcp_f32_e32 v135, v135
	v_rcp_f32_e32 v136, v136
	v_rcp_f32_e32 v137, v137
	v_pk_mul_f32 v[102:103], v[102:103], v[134:135]
	v_pk_mul_f32 v[104:105], v[104:105], v[136:137]
	v_pk_mul_f32 v[98:99], v[98:99], v[102:103]
	v_pk_mul_f32 v[100:101], v[100:101], v[104:105]
	v_cvt_pk_bf16_f32 v194, v98, v99
	v_cvt_pk_bf16_f32 v195, v100, v101
	global_store_dwordx4 v[196:197], v[192:195], off
	v_lshl_add_u64 v[138:139], v[196:197], 0, s[6:7]
	v_pk_mul_f32 v[94:95], v[94:95], v[170:171] op_sel:[0,1]
	v_pk_mul_f32 v[96:97], v[96:97], v[170:171] op_sel:[0,1]
	v_pk_mul_f32 v[90:91], v[90:91], v[170:171] op_sel:[0,1]
	v_pk_mul_f32 v[92:93], v[92:93], v[170:171] op_sel:[0,1]
	v_pk_mul_f32 v[134:135], v[94:95], v[198:199]
	v_pk_mul_f32 v[136:137], v[96:97], v[198:199]
	v_exp_f32_e32 v134, v134
	v_exp_f32_e32 v135, v135
	v_exp_f32_e32 v136, v136
	v_exp_f32_e32 v137, v137
	v_pk_add_f32 v[134:135], v[134:135], 1.0 op_sel_hi:[1,0]
	v_pk_add_f32 v[136:137], v[136:137], 1.0 op_sel_hi:[1,0]
	v_rcp_f32_e32 v134, v134
	v_rcp_f32_e32 v135, v135
	v_rcp_f32_e32 v136, v136
	v_rcp_f32_e32 v137, v137
	v_pk_mul_f32 v[94:95], v[94:95], v[134:135]
	v_pk_mul_f32 v[96:97], v[96:97], v[136:137]
	v_pk_mul_f32 v[90:91], v[90:91], v[94:95]
	v_pk_mul_f32 v[92:93], v[92:93], v[96:97]
	v_cvt_pk_bf16_f32 v188, v90, v91
	v_cvt_pk_bf16_f32 v189, v92, v93
	v_pk_mul_f32 v[86:87], v[86:87], v[170:171] op_sel:[0,1]
	v_pk_mul_f32 v[88:89], v[88:89], v[170:171] op_sel:[0,1]
	v_pk_mul_f32 v[82:83], v[82:83], v[170:171] op_sel:[0,1]
	v_pk_mul_f32 v[84:85], v[84:85], v[170:171] op_sel:[0,1]
; __device__ __forceinline__ u32x4 pack8(const float* v) { u32x4 w; w.x = cvtpk(v[0], v[1]); w.y = cvtpk(v[2], v[3]); w.z = cvtpk(v[4], v[5]); w.w = cvtpk(v[6], v[7]); return w; }
; __device__ __forceinline__ float sigm(float x) { return __builtin_amdgcn_rcpf(1.f + __expf(-x)); }
; __device__ __forceinline__ float siluf_(float x) { return x * sigm(x); }
;     __device__ __forceinline__ void operator()(const pg8::f32x4 (&acc)[2][2][4][2], const pg8::Unit& u, int wr, int wc, int fr, int fq) const {
;     ...
;         bf16* O = (bf16*)(w_ + WS_HFF);
;         const int row0 = u.pm * 256 + wr * 64 + fr_, col0 = u.pn * 128 + wc * 32 + fq_ * 8;
;         EPI_RSTD(rs)
; #pragma unroll
;         for (int ai = 0; ai < 2; ++ai)
; #pragma unroll
;             for (int m = 0; m < 4; ++m) {
;                 float v[8]; const float r = rs[ai][m];
; #pragma unroll
;                 for (int n = 0; n < 2; ++n)
; #pragma unroll
;                     for (int j = 0; j < 4; ++j) v[n * 4 + j] = siluf_(acc[ai][0][m][n][j] * r) * (acc[ai][1][m][n][j] * r);
;                 *(u32x4*)(O + (size_t)(row0 + ai * 128 + m * 16) * FF + col0) = pack8(v);
;             }
	v_pk_mul_f32 v[134:135], v[86:87], v[198:199]
	v_pk_mul_f32 v[136:137], v[88:89], v[198:199]
	v_exp_f32_e32 v134, v134
	v_exp_f32_e32 v135, v135
	v_exp_f32_e32 v136, v136
	v_exp_f32_e32 v137, v137
	v_pk_add_f32 v[134:135], v[134:135], 1.0 op_sel_hi:[1,0]
	v_pk_add_f32 v[136:137], v[136:137], 1.0 op_sel_hi:[1,0]
	v_rcp_f32_e32 v134, v134
	v_rcp_f32_e32 v135, v135
	v_rcp_f32_e32 v136, v136
	v_rcp_f32_e32 v137, v137
	v_pk_mul_f32 v[86:87], v[86:87], v[134:135]
	v_pk_mul_f32 v[88:89], v[88:89], v[136:137]
	v_pk_mul_f32 v[82:83], v[82:83], v[86:87]
	v_pk_mul_f32 v[84:85], v[84:85], v[88:89]
	v_cvt_pk_bf16_f32 v190, v82, v83
	v_cvt_pk_bf16_f32 v191, v84, v85
	global_store_dwordx4 v[138:139], v[188:191], off
	v_lshl_add_u64 v[196:197], v[138:139], 0, s[6:7]
	v_pk_mul_f32 v[78:79], v[78:79], v[170:171] op_sel_hi:[1,0]
	v_pk_mul_f32 v[80:81], v[80:81], v[170:171] op_sel_hi:[1,0]
	v_pk_mul_f32 v[74:75], v[74:75], v[170:171] op_sel_hi:[1,0]
	v_pk_mul_f32 v[76:77], v[76:77], v[170:171] op_sel_hi:[1,0]
	v_pk_mul_f32 v[134:135], v[78:79], v[198:199]
	v_pk_mul_f32 v[136:137], v[80:81], v[198:199]
	v_exp_f32_e32 v134, v134
	v_exp_f32_e32 v135, v135
	v_exp_f32_e32 v136, v136
	v_exp_f32_e32 v137, v137
	v_pk_add_f32 v[134:135], v[134:135], 1.0 op_sel_hi:[1,0]
	v_pk_add_f32 v[136:137], v[136:137], 1.0 op_sel_hi:[1,0]
	v_rcp_f32_e32 v134, v134
	v_rcp_f32_e32 v135, v135
	v_rcp_f32_e32 v136, v136
	v_rcp_f32_e32 v137, v137
	v_pk_mul_f32 v[78:79], v[78:79], v[134:135]
	v_pk_mul_f32 v[80:81], v[80:81], v[136:137]
	v_pk_mul_f32 v[74:75], v[74:75], v[78:79]
	v_pk_mul_f32 v[76:77], v[76:77], v[80:81]
	v_cvt_pk_bf16_f32 v192, v74, v75
	v_cvt_pk_bf16_f32 v193, v76, v77
	v_pk_mul_f32 v[70:71], v[70:71], v[170:171] op_sel_hi:[1,0]
	v_pk_mul_f32 v[72:73], v[72:73], v[170:171] op_sel_hi:[1,0]
	v_pk_mul_f32 v[66:67], v[66:67], v[170:171] op_sel_hi:[1,0]
	v_pk_mul_f32 v[68:69], v[68:69], v[170:171] op_sel_hi:[1,0]
	v_pk_mul_f32 v[134:135], v[70:71], v[198:199]
	v_pk_mul_f32 v[136:137], v[72:73], v[198:199]
	v_exp_f32_e32 v134, v134
	v_exp_f32_e32 v135, v135
	v_exp_f32_e32 v136, v136
	v_exp_f32_e32 v137, v137
	v_pk_add_f32 v[134:135], v[134:135], 1.0 op_sel_hi:[1,0]
	v_pk_add_f32 v[136:137], v[136:137], 1.0 op_sel_hi:[1,0]
	v_rcp_f32_e32 v134, v134
	v_rcp_f32_e32 v135, v135
	v_rcp_f32_e32 v136, v136
	v_rcp_f32_e32 v137, v137
	v_pk_mul_f32 v[70:71], v[70:71], v[134:135]
	v_pk_mul_f32 v[72:73], v[72:73], v[136:137]
	v_pk_mul_f32 v[66:67], v[66:67], v[70:71]
	v_pk_mul_f32 v[68:69], v[68:69], v[72:73]
	v_cvt_pk_bf16_f32 v194, v66, v67
	v_cvt_pk_bf16_f32 v195, v68, v69
	global_store_dwordx4 v[196:197], v[192:195], off
	s_mul_i32 s6, s84, 0x50
	s_mov_b32 s7, 0
	v_lshl_add_u64 v[138:139], v[196:197], 0, s[6:7]
	v_pk_mul_f32 v[62:63], v[62:63], v[166:167] op_sel:[0,1]
	v_pk_mul_f32 v[64:65], v[64:65], v[166:167] op_sel:[0,1]
	v_pk_mul_f32 v[58:59], v[58:59], v[166:167] op_sel:[0,1]
	v_pk_mul_f32 v[60:61], v[60:61], v[166:167] op_sel:[0,1]
	v_pk_mul_f32 v[134:135], v[62:63], v[198:199]
	v_pk_mul_f32 v[136:137], v[64:65], v[198:199]
	v_exp_f32_e32 v134, v134
	v_exp_f32_e32 v135, v135
	v_exp_f32_e32 v136, v136
	v_exp_f32_e32 v137, v137
	v_pk_add_f32 v[134:135], v[134:135], 1.0 op_sel_hi:[1,0]
	v_pk_add_f32 v[136:137], v[136:137], 1.0 op_sel_hi:[1,0]
	v_rcp_f32_e32 v134, v134
	v_rcp_f32_e32 v135, v135
	v_rcp_f32_e32 v136, v136
	v_rcp_f32_e32 v137, v137
	v_pk_mul_f32 v[62:63], v[62:63], v[134:135]
	v_pk_mul_f32 v[64:65], v[64:65], v[136:137]
	v_pk_mul_f32 v[58:59], v[58:59], v[62:63]
	v_pk_mul_f32 v[60:61], v[60:61], v[64:65]
	v_cvt_pk_bf16_f32 v188, v58, v59
	v_cvt_pk_bf16_f32 v189, v60, v61
	v_pk_mul_f32 v[54:55], v[54:55], v[166:167] op_sel:[0,1]
	v_pk_mul_f32 v[56:57], v[56:57], v[166:167] op_sel:[0,1]
	v_pk_mul_f32 v[50:51], v[50:51], v[166:167] op_sel:[0,1]
	v_pk_mul_f32 v[52:53], v[52:53], v[166:167] op_sel:[0,1]
	v_pk_mul_f32 v[134:135], v[54:55], v[198:199]
	v_pk_mul_f32 v[136:137], v[56:57], v[198:199]
	v_exp_f32_e32 v134, v134
	v_exp_f32_e32 v135, v135
	v_exp_f32_e32 v136, v136
	v_exp_f32_e32 v137, v137
	v_pk_add_f32 v[134:135], v[134:135], 1.0 op_sel_hi:[1,0]
	v_pk_add_f32 v[136:137], v[136:137], 1.0 op_sel_hi:[1,0]
	v_rcp_f32_e32 v134, v134
	v_rcp_f32_e32 v135, v135
	v_rcp_f32_e32 v136, v136
	v_rcp_f32_e32 v137, v137
	v_pk_mul_f32 v[54:55], v[54:55], v[134:135]
	v_pk_mul_f32 v[56:57], v[56:57], v[136:137]
	v_pk_mul_f32 v[50:51], v[50:51], v[54:55]
	v_pk_mul_f32 v[52:53], v[52:53], v[56:57]
	v_cvt_pk_bf16_f32 v190, v50, v51
	v_cvt_pk_bf16_f32 v191, v52, v53
	global_store_dwordx4 v[138:139], v[188:191], off
	s_lshl_b32 s6, s84, 4
	s_mov_b32 s7, 0
	v_lshl_add_u64 v[196:197], v[138:139], 0, s[6:7]
	v_pk_mul_f32 v[46:47], v[46:47], v[166:167] op_sel_hi:[1,0]
	v_pk_mul_f32 v[48:49], v[48:49], v[166:167] op_sel_hi:[1,0]
	v_pk_mul_f32 v[42:43], v[42:43], v[166:167] op_sel_hi:[1,0]
	v_pk_mul_f32 v[44:45], v[44:45], v[166:167] op_sel_hi:[1,0]
	v_pk_mul_f32 v[134:135], v[46:47], v[198:199]
	v_pk_mul_f32 v[136:137], v[48:49], v[198:199]
	v_exp_f32_e32 v134, v134
	v_exp_f32_e32 v135, v135
	v_exp_f32_e32 v136, v136
	v_exp_f32_e32 v137, v137
	v_pk_add_f32 v[134:135], v[134:135], 1.0 op_sel_hi:[1,0]
	v_pk_add_f32 v[136:137], v[136:137], 1.0 op_sel_hi:[1,0]
	v_rcp_f32_e32 v134, v134
; #define PG8_BAR __builtin_amdgcn_s_barrier()
; __device__ __forceinline__ float siluf_(float x) { return x * sigm(x); }
; __device__ __forceinline__ u32x4 pack8(const float* v) { u32x4 w; w.x = cvtpk(v[0], v[1]); w.y = cvtpk(v[2], v[3]); w.z = cvtpk(v[4], v[5]); w.w = cvtpk(v[6], v[7]); return w; }
; template <class Epi, class Sched, bool ALIGN_EPI = false, bool SP2 = false>
; __device__ __forceinline__ void gemm_phase(PG8_LAS unsigned char* lds, const Gemm g, const Sched& S, const Epi& E) {
;     ...
;         if constexpr (ALIGN_EPI) { if (wr == 1) PG8_BAR; }
;     __device__ __forceinline__ void operator()(const pg8::f32x4 (&acc)[2][2][4][2], const pg8::Unit& u, int wr, int wc, int fr, int fq) const {
;     ...
;         bf16* O = (bf16*)(w_ + WS_HFF);
;         const int row0 = u.pm * 256 + wr * 64 + fr_, col0 = u.pn * 128 + wc * 32 + fq_ * 8;
;         EPI_RSTD(rs)
; #pragma unroll
;         for (int ai = 0; ai < 2; ++ai)
; #pragma unroll
;             for (int m = 0; m < 4; ++m) {
;                 float v[8]; const float r = rs[ai][m];
; #pragma unroll
;                 for (int n = 0; n < 2; ++n)
; #pragma unroll
;                     for (int j = 0; j < 4; ++j) v[n * 4 + j] = siluf_(acc[ai][0][m][n][j] * r) * (acc[ai][1][m][n][j] * r);
;                 *(u32x4*)(O + (size_t)(row0 + ai * 128 + m * 16) * FF + col0) = pack8(v);
;             }
	v_rcp_f32_e32 v135, v135
	v_rcp_f32_e32 v136, v136
	v_rcp_f32_e32 v137, v137
	v_pk_mul_f32 v[46:47], v[46:47], v[134:135]
	v_pk_mul_f32 v[48:49], v[48:49], v[136:137]
	v_pk_mul_f32 v[42:43], v[42:43], v[46:47]
	v_pk_mul_f32 v[44:45], v[44:45], v[48:49]
	v_cvt_pk_bf16_f32 v192, v42, v43
	v_cvt_pk_bf16_f32 v193, v44, v45
	v_pk_mul_f32 v[38:39], v[38:39], v[166:167] op_sel_hi:[1,0]
	v_pk_mul_f32 v[40:41], v[40:41], v[166:167] op_sel_hi:[1,0]
	v_pk_mul_f32 v[34:35], v[34:35], v[166:167] op_sel_hi:[1,0]
	v_pk_mul_f32 v[36:37], v[36:37], v[166:167] op_sel_hi:[1,0]
	v_pk_mul_f32 v[134:135], v[38:39], v[198:199]
	v_pk_mul_f32 v[136:137], v[40:41], v[198:199]
	v_exp_f32_e32 v134, v134
	v_exp_f32_e32 v135, v135
	v_exp_f32_e32 v136, v136
	v_exp_f32_e32 v137, v137
	v_pk_add_f32 v[134:135], v[134:135], 1.0 op_sel_hi:[1,0]
	v_pk_add_f32 v[136:137], v[136:137], 1.0 op_sel_hi:[1,0]
	v_rcp_f32_e32 v134, v134
	v_rcp_f32_e32 v135, v135
	v_rcp_f32_e32 v136, v136
	v_rcp_f32_e32 v137, v137
	v_pk_mul_f32 v[38:39], v[38:39], v[134:135]
	v_pk_mul_f32 v[40:41], v[40:41], v[136:137]
	v_pk_mul_f32 v[34:35], v[34:35], v[38:39]
	v_pk_mul_f32 v[36:37], v[36:37], v[40:41]
	v_cvt_pk_bf16_f32 v194, v34, v35
	v_cvt_pk_bf16_f32 v195, v36, v37
	global_store_dwordx4 v[196:197], v[192:195], off
	v_lshl_add_u64 v[138:139], v[196:197], 0, s[6:7]
	v_pk_mul_f32 v[30:31], v[30:31], v[130:131] op_sel:[0,1]
	v_pk_mul_f32 v[32:33], v[32:33], v[130:131] op_sel:[0,1]
	v_pk_mul_f32 v[26:27], v[26:27], v[130:131] op_sel:[0,1]
	v_pk_mul_f32 v[28:29], v[28:29], v[130:131] op_sel:[0,1]
	v_pk_mul_f32 v[134:135], v[30:31], v[198:199]
	v_pk_mul_f32 v[136:137], v[32:33], v[198:199]
	v_exp_f32_e32 v134, v134
	v_exp_f32_e32 v135, v135
	v_exp_f32_e32 v136, v136
	v_exp_f32_e32 v137, v137
	v_pk_add_f32 v[134:135], v[134:135], 1.0 op_sel_hi:[1,0]
	v_pk_add_f32 v[136:137], v[136:137], 1.0 op_sel_hi:[1,0]
	v_rcp_f32_e32 v134, v134
	v_rcp_f32_e32 v135, v135
	v_rcp_f32_e32 v136, v136
	v_rcp_f32_e32 v137, v137
	v_pk_mul_f32 v[30:31], v[30:31], v[134:135]
	v_pk_mul_f32 v[32:33], v[32:33], v[136:137]
	v_pk_mul_f32 v[26:27], v[26:27], v[30:31]
	v_pk_mul_f32 v[28:29], v[28:29], v[32:33]
	v_cvt_pk_bf16_f32 v188, v26, v27
	v_cvt_pk_bf16_f32 v189, v28, v29
	v_pk_mul_f32 v[22:23], v[22:23], v[130:131] op_sel:[0,1]
	v_pk_mul_f32 v[24:25], v[24:25], v[130:131] op_sel:[0,1]
	v_pk_mul_f32 v[18:19], v[18:19], v[130:131] op_sel:[0,1]
	v_pk_mul_f32 v[20:21], v[20:21], v[130:131] op_sel:[0,1]
	v_pk_mul_f32 v[134:135], v[22:23], v[198:199]
	v_pk_mul_f32 v[136:137], v[24:25], v[198:199]
	v_exp_f32_e32 v134, v134
	v_exp_f32_e32 v135, v135
	v_exp_f32_e32 v136, v136
	v_exp_f32_e32 v137, v137
	v_pk_add_f32 v[134:135], v[134:135], 1.0 op_sel_hi:[1,0]
	v_pk_add_f32 v[136:137], v[136:137], 1.0 op_sel_hi:[1,0]
	v_rcp_f32_e32 v134, v134
	v_rcp_f32_e32 v135, v135
	v_rcp_f32_e32 v136, v136
	v_rcp_f32_e32 v137, v137
	v_pk_mul_f32 v[22:23], v[22:23], v[134:135]
	v_pk_mul_f32 v[24:25], v[24:25], v[136:137]
	v_pk_mul_f32 v[18:19], v[18:19], v[22:23]
	v_pk_mul_f32 v[20:21], v[20:21], v[24:25]
	v_cvt_pk_bf16_f32 v190, v18, v19
	v_cvt_pk_bf16_f32 v191, v20, v21
	global_store_dwordx4 v[138:139], v[188:191], off
	v_lshl_add_u64 v[196:197], v[138:139], 0, s[6:7]
	v_pk_mul_f32 v[14:15], v[14:15], v[130:131] op_sel_hi:[1,0]
	v_pk_mul_f32 v[16:17], v[16:17], v[130:131] op_sel_hi:[1,0]
	v_pk_mul_f32 v[10:11], v[10:11], v[130:131] op_sel_hi:[1,0]
	v_pk_mul_f32 v[12:13], v[12:13], v[130:131] op_sel_hi:[1,0]
	v_pk_mul_f32 v[134:135], v[14:15], v[198:199]
	v_pk_mul_f32 v[136:137], v[16:17], v[198:199]
	v_exp_f32_e32 v134, v134
	v_exp_f32_e32 v135, v135
	v_exp_f32_e32 v136, v136
	v_exp_f32_e32 v137, v137
	v_pk_add_f32 v[134:135], v[134:135], 1.0 op_sel_hi:[1,0]
	v_pk_add_f32 v[136:137], v[136:137], 1.0 op_sel_hi:[1,0]
	v_rcp_f32_e32 v134, v134
	v_rcp_f32_e32 v135, v135
	v_rcp_f32_e32 v136, v136
	v_rcp_f32_e32 v137, v137
	v_pk_mul_f32 v[14:15], v[14:15], v[134:135]
	v_pk_mul_f32 v[16:17], v[16:17], v[136:137]
	v_pk_mul_f32 v[10:11], v[10:11], v[14:15]
	v_pk_mul_f32 v[12:13], v[12:13], v[16:17]
	v_cvt_pk_bf16_f32 v192, v10, v11
	v_cvt_pk_bf16_f32 v193, v12, v13
	v_pk_mul_f32 v[6:7], v[6:7], v[130:131] op_sel_hi:[1,0]
	v_pk_mul_f32 v[8:9], v[8:9], v[130:131] op_sel_hi:[1,0]
	v_pk_mul_f32 v[2:3], v[2:3], v[130:131] op_sel_hi:[1,0]
	v_pk_mul_f32 v[4:5], v[4:5], v[130:131] op_sel_hi:[1,0]
	v_pk_mul_f32 v[134:135], v[6:7], v[198:199]
	v_pk_mul_f32 v[136:137], v[8:9], v[198:199]
	v_exp_f32_e32 v134, v134
	v_exp_f32_e32 v135, v135
	v_exp_f32_e32 v136, v136
	v_exp_f32_e32 v137, v137
	v_pk_add_f32 v[134:135], v[134:135], 1.0 op_sel_hi:[1,0]
	v_pk_add_f32 v[136:137], v[136:137], 1.0 op_sel_hi:[1,0]
	v_rcp_f32_e32 v134, v134
	v_rcp_f32_e32 v135, v135
	v_rcp_f32_e32 v136, v136
	v_rcp_f32_e32 v137, v137
	v_pk_mul_f32 v[6:7], v[6:7], v[134:135]
	v_pk_mul_f32 v[8:9], v[8:9], v[136:137]
	v_pk_mul_f32 v[2:3], v[2:3], v[6:7]
	v_pk_mul_f32 v[4:5], v[4:5], v[8:9]
	v_cvt_pk_bf16_f32 v194, v2, v3
	v_cvt_pk_bf16_f32 v195, v4, v5
	s_andn2_b64 vcc, exec, s[0:1]
	s_mov_b64 s[6:7], -1
	global_store_dwordx4 v[196:197], v[192:195], off
	s_cbranch_vccnz .LBB0_1389
	s_andn2_b64 vcc, exec, s[4:5]
	s_cbranch_vccnz .LBB0_1388
	s_barrier
	s_branch .LBB0_1388
